# attn QK LDS-read pipelining + CU-mate half-iteration stagger + GEMM k-loop LDS-read reschedule (direction alternation removed: made outputs order-dependent)
# baseline (speedup 1.0000x reference)
; DI unsigned xb_xcc_id() { return (unsigned)__builtin_amdgcn_s_getreg((3 << 11) | 20) & 0xFu; }
; DI void run_phase(const Params& pin, int ph, unsigned char* lds, int* s_item) {
;     ...
;     case 4: {
;       unsigned* ctr = (unsigned*)(p.ws + OFF_CTR) + ps * 8;
;       const int myx = (int)(xb_xcc_id() & 7u);
;       for (int dx = 0; dx < 8; ++dx) {
;         const int x = (myx + dx) & 7;
;         for (;;) {
;           if (tid == 0) *s_item = (int)atomicAdd(ctr + x, 1u);
;           __syncthreads();
;           const int j = *s_item;
;           __syncthreads();
;           if (j >= 193) break;
;           if (j == 0) scan_item(p, x, lds);
;           else {
;             const int g = (j - 1) / 3, k = (j - 1) % 3;
;             if (k < 2) diffmap_item(p, l, x >> 1, x & 1, 127 - 2 * g - k, lds);
;             else mla_item(p, l, x >> 1, 127 - 2 * g - (x & 1), lds);
.LBB0_345:
	s_andn2_b64 vcc, exec, s[0:1]
	s_cbranch_vccnz .LBB0_994
	v_readlane_b32 s0, v254, 53
	s_cmp_lt_i32 s0, 2
	s_mov_b64 s[0:1], -1
	s_cbranch_scc1 .LBB0_917
	v_readlane_b32 s0, v254, 53
	s_cmp_lt_i32 s0, 3
	s_mov_b64 s[0:1], -1
	s_cbranch_scc1 .LBB0_839
	v_readlane_b32 s0, v254, 53
	s_cmp_gt_i32 s0, 3
	s_mov_b64 s[0:1], -1
	s_cbranch_scc0 .LBB0_445
	v_writelane_b32 v254, s78, 56
	s_lshl_b32 s0, s42, 3
	s_ashr_i32 s1, s0, 31
	v_writelane_b32 v254, s79, 57
	v_writelane_b32 v254, s18, 54
	s_lshl_b64 s[0:1], s[0:1], 2
	v_writelane_b32 v254, s19, 55
	s_add_u32 s0, s94, s0
	v_writelane_b32 v254, s0, 58
	s_addc_u32 s0, s95, s1
	s_getreg_b32 s56, hwreg(HW_REG_XCC_ID, 0, 4)
	v_writelane_b32 v254, s0, 59
	s_and_b32 s0, s56, 15
	v_writelane_b32 v254, s0, 60
	s_add_u32 s0, s94, 0x1b900000
	v_writelane_b32 v254, s0, 61
	s_addc_u32 s0, s95, 0
	v_writelane_b32 v254, s0, 62
	s_add_u32 s0, s94, 0x1ad00000
	v_writelane_b32 v254, s0, 63
	s_addc_u32 s0, s95, 0
	s_mov_b32 s4, 0
	v_writelane_b32 v255, s0, 0
	s_add_u32 s0, s94, 0x1a100000
	v_writelane_b32 v255, s0, 1
	s_addc_u32 s0, s95, 0
	v_writelane_b32 v255, s0, 2
	s_add_u32 s0, s94, 0x16100000
	v_writelane_b32 v255, s0, 3
	s_addc_u32 s0, s95, 0
	v_writelane_b32 v255, s0, 4
	v_readlane_b32 s0, v254, 50
	s_lshl_b32 s33, s0, 6
	s_add_u32 s0, s94, 0x19100000
	v_writelane_b32 v255, s0, 5
	s_addc_u32 s0, s95, 0
	v_writelane_b32 v255, s0, 6
	s_add_u32 s0, s94, 0x6c00000
	v_writelane_b32 v255, s0, 7
	s_addc_u32 s0, s95, 0
	v_writelane_b32 v255, s0, 8
	s_add_u32 s0, s94, 0x6c00400
	v_writelane_b32 v255, s0, 9
	s_addc_u32 s0, s95, 0
	v_writelane_b32 v255, s0, 10
	s_add_u32 s0, s94, 0xb400000
	v_writelane_b32 v255, s0, 11
	s_addc_u32 s0, s95, 0
	v_writelane_b32 v255, s0, 12
	s_add_u32 s0, s94, 0x1c900000
	v_writelane_b32 v255, s0, 13
	s_addc_u32 s0, s95, 0
	v_writelane_b32 v255, s0, 14
	s_add_u32 s0, s94, 0xd400000
	v_writelane_b32 v255, s0, 15
	s_addc_u32 s0, s95, 0
	v_writelane_b32 v255, s0, 16
	s_add_u32 s0, s94, 0x1e100000
	v_writelane_b32 v255, s0, 17
	s_addc_u32 s0, s95, 0
	s_bitcmp1_b32 s56, 0
	v_cmp_eq_u32_e64 s[38:39], 0, v220
	v_writelane_b32 v255, s0, 18
	s_cselect_b64 s[2:3], -1, 0
	s_branch .LBB0_351

; DI int otid() { int t = (int)__builtin_amdgcn_workitem_id_x(); asm volatile("" : "+v"(t)); return t; }
; #define ATT_LOADK(rk_, k0_) { _Pragma("unroll") for (int i = 0; i < NKC; ++i) { int c = tid + 256 * i, row = c / CPR, kc = (c % CPR) * 8; rk_[i] = *(const bf16x8*)(Kp + (size_t)((k0_) + row) * ldk + kc); } }
; #define ATT_LOADV(rv_, k0_) { _Pragma("unroll") for (int i = 0; i < 4; ++i) { int c = tid + 256 * i, row = c >> 3, tc = (c & 7) * 8; rv_[i] = *(const bf16x8*)(Vt + (size_t)row * TT + (k0_) + tc); } }
; #define ATT_STOREK(rk_, buf_) { bf16_t* sK_ = (bf16_t*)(ldsb + (buf_) * ATT_BUF); _Pragma("unroll") for (int i = 0; i < NKC; ++i) { int c = tid + 256 * i, row = c / CPR, kc = (c % CPR) * 8; *(bf16x8*)(sK_ + row * KST + kc) = rk_[i]; } }
; #define ATT_STOREV(rv_, buf_) { bf16_t* sV_ = (bf16_t*)(ldsb + (buf_) * ATT_BUF + 13312); _Pragma("unroll") for (int i = 0; i < 4; ++i) { int c = tid + 256 * i, row = c >> 3, tc = (c & 7) * 8; *(bf16x8*)(sV_ + row * 72 + tc) = rv_[i]; } }
; template <int DK, bool FIXED>
; DI void attn_pass(f32x16 (&O)[4], const bf16_t* __restrict__ Qw  , int ldq, const bf16_t* __restrict__ Kp, int ldk,
;                   const bf16_t* __restrict__ Vt, int ntb, int ntw, unsigned char* ldsb, float M2) {
;     ...
;   bf16x8 qf[KS];
; #pragma unroll
;   for (int ks = 0; ks < KS; ++ks) qf[ks] = *(const bf16x8*)(Qw + (size_t)l31 * ldq + ks * 16 + hf * 8);
; #pragma unroll
;   for (int d = 0; d < 4; ++d)
; #pragma unroll
;     for (int r = 0; r < 16; ++r) O[d][r] = 0.f;
;   float ps0 = 0.f, ps1 = 0.f, ps2 = 0.f, ps3 = 0.f;
;   bf16x8 rk[NKC], rv[4];
;     ...
;   bf16x8 pfA[4], pfB[4];
;   {
;     bf16x8 rkb[NKC];
;     ATT_LOADK(rk, 0) ATT_LOADK(rkb, 64) ATT_LOADV(rv, 0)
;     ATT_STOREK(rk, 0) ATT_STOREK(rkb, 1) ATT_STOREV(rv, 0)
; DI void mla_item(const Params& p, int l, int h, int qt, unsigned char* lds) {
;     ...
;   const int lane = otid() & 63;
;   float wq = fmaxf(fabsf(p.mqn[l * 96 + lane]), lane < 32 ? fabsf(p.mqn[l * 96 + 64 + lane]) : 0.f);
;   float wk = fmaxf(fabsf(p.mkn[l * 96 + lane]), lane < 32 ? fabsf(p.mkn[l * 96 + 64 + lane]) : 0.f);
; #pragma unroll
;   for (int o = 32; o >= 1; o >>= 1) { wq = fmaxf(wq, __shfl_xor(wq, o)); wk = fmaxf(wk, __shfl_xor(wk, o)); }
;   const float M2 = 9.797959f * LOG2E * 1.03f * wq * wk;
;   attn_pass<96, true>(O, QB + (size_t)row0 * 384 + h * 96, 384, KB + h * 96, 384, VT, ntb, ntw, lds, fminf(M2, 60.f));
.LBB0_365:
	s_or_b64 exec, exec, s[0:1]
	v_max_f32_e32 v0, v5, v5
	s_waitcnt vmcnt(1)
	v_max_f32_e64 v3, |v3|, |v3|
	v_max_f32_e32 v0, v3, v0
	v_max_f32_e32 v2, v2, v2
	s_waitcnt vmcnt(0)
	v_max_f32_e64 v3, |v4|, |v4|
	v_max_f32_e32 v2, v3, v2
	v_and_b32_e32 v3, 64, v227
	v_add_u32_e32 v3, 64, v3
	v_xor_b32_e32 v4, 32, v227
	v_cmp_lt_i32_e32 vcc, v4, v3
	s_or_b32 s1, s8, s5
	v_mov_b32_e32 v15, v201
	v_cndmask_b32_e32 v4, v227, v4, vcc
	v_lshlrev_b32_e32 v235, 2, v4
	ds_bpermute_b32 v4, v235, v0
	s_sub_i32 s0, 0x7f, s1
	v_mov_b32_e32 v205, v1
	v_and_b32_e32 v9, 31, v15
	s_waitcnt lgkmcnt(0)
	v_max_f32_e32 v4, v4, v4
	v_max_f32_e32 v0, v0, v4
	ds_bpermute_b32 v4, v235, v2
	v_bfe_u32 v14, v15, 5, 1
	v_lshlrev_b32_e32 v204, 4, v14
	s_mov_b32 s9, 0x2aaaaaab
	v_mov_b64_e32 v[24:25], s[44:45]
	s_waitcnt lgkmcnt(0)
	v_max_f32_e32 v4, v4, v4
	v_max_f32_e32 v2, v2, v4
	v_xor_b32_e32 v4, 16, v227
	v_cmp_lt_i32_e32 vcc, v4, v3
	v_add_u32_e32 v32, 0x100, v15
	v_add_u32_e32 v36, 0x200, v15
	v_cndmask_b32_e32 v4, v227, v4, vcc
	v_lshlrev_b32_e32 v4, 2, v4
	ds_bpermute_b32 v5, v4, v0
	ds_bpermute_b32 v4, v4, v2
	v_ashrrev_i32_e32 v44, 3, v15
	v_ashrrev_i32_e32 v46, 3, v32
	v_ashrrev_i32_e32 v48, 3, v36
	s_waitcnt lgkmcnt(1)
	v_max_f32_e32 v5, v5, v5
	s_waitcnt lgkmcnt(0)
	v_max_f32_e32 v4, v4, v4
	v_max_f32_e32 v2, v2, v4
	v_xor_b32_e32 v4, 8, v227
	v_cmp_lt_i32_e32 vcc, v4, v3
	v_max_f32_e32 v0, v0, v5
	v_ashrrev_i32_e32 v45, 31, v44
	v_cndmask_b32_e32 v4, v227, v4, vcc
	v_lshlrev_b32_e32 v4, 2, v4
	ds_bpermute_b32 v5, v4, v0
	ds_bpermute_b32 v4, v4, v2
	v_ashrrev_i32_e32 v47, 31, v46
	v_ashrrev_i32_e32 v49, 31, v48
	v_lshlrev_b64 v[208:209], 15, v[44:45]
	s_waitcnt lgkmcnt(1)
	v_max_f32_e32 v5, v5, v5
	s_waitcnt lgkmcnt(0)
	v_max_f32_e32 v4, v4, v4
	v_max_f32_e32 v2, v2, v4
	v_xor_b32_e32 v4, 4, v227
	v_cmp_lt_i32_e32 vcc, v4, v3
	v_max_f32_e32 v0, v0, v5
	v_lshlrev_b64 v[210:211], 15, v[46:47]
	v_cndmask_b32_e32 v4, v227, v4, vcc
	v_lshlrev_b32_e32 v4, 2, v4
	ds_bpermute_b32 v5, v4, v0
	ds_bpermute_b32 v4, v4, v2
	v_lshlrev_b64 v[212:213], 15, v[48:49]
	s_cmpk_eq_i32 s1, 0x7f
	s_waitcnt lgkmcnt(1)
	v_max_f32_e32 v5, v5, v5
	s_waitcnt lgkmcnt(0)
	v_max_f32_e32 v4, v4, v4
	v_max_f32_e32 v2, v2, v4
	v_xor_b32_e32 v4, 2, v227
	v_cmp_lt_i32_e32 vcc, v4, v3
	v_max_f32_e32 v0, v0, v5
	s_nop 0
	v_cndmask_b32_e32 v4, v227, v4, vcc
	v_lshlrev_b32_e32 v4, 2, v4
	ds_bpermute_b32 v5, v4, v0
	s_waitcnt lgkmcnt(0)
	v_max_f32_e32 v5, v5, v5
	v_max_f32_e32 v10, v0, v5
	ds_bpermute_b32 v0, v4, v2
	s_waitcnt lgkmcnt(0)
	v_max_f32_e32 v0, v0, v0
	v_max_f32_e32 v11, v2, v0
	v_xor_b32_e32 v0, 1, v227
	v_cmp_lt_i32_e32 vcc, v0, v3
	v_mov_b64_e32 v[2:3], s[24:25]
	s_nop 0
	v_cndmask_b32_e32 v0, v227, v0, vcc
	v_lshlrev_b32_e32 v0, 2, v0
	ds_bpermute_b32 v13, v0, v10
	ds_bpermute_b32 v12, v0, v11
	v_ashrrev_i32_e32 v0, 1, v8
	v_and_b32_e32 v0, 0xffffffe0, v0
	v_lshl_add_u32 v202, s0, 7, v0
	v_mul_u32_u24_e32 v0, 0x180, v9
	v_mad_i64_i32 v[2:3], s[10:11], v202, s86, v[2:3]
	v_lshlrev_b32_e32 v0, 1, v0
	v_lshl_add_u64 v[2:3], v[2:3], 0, v[0:1]
	v_lshl_add_u64 v[2:3], v[2:3], 0, v[204:205]
	v_mul_hi_i32 v0, v15, s9
	global_load_dwordx4 v[128:131], v[2:3], off
	global_load_dwordx4 v[132:135], v[2:3], off offset:32
	global_load_dwordx4 v[136:139], v[2:3], off offset:64
	global_load_dwordx4 v[140:143], v[2:3], off offset:96
	global_load_dwordx4 v[144:147], v[2:3], off offset:128
	global_load_dwordx4 v[148:151], v[2:3], off offset:160
	v_lshrrev_b32_e32 v2, 31, v0
	v_ashrrev_i32_e32 v0, 1, v0
	v_add_u32_e32 v205, v0, v2
	v_mul_lo_u32 v0, v205, 12
	v_sub_u32_e32 v52, v15, v0
	v_lshlrev_b32_e32 v2, 3, v52
	v_ashrrev_i32_e32 v3, 31, v2
	v_mad_i64_i32 v[4:5], s[10:11], v205, s86, v[24:25]
	v_lshlrev_b64 v[16:17], 1, v[2:3]
	v_lshl_add_u64 v[4:5], v[4:5], 0, v[16:17]
	v_mul_hi_i32 v0, v32, s9
	global_load_dwordx4 v[152:155], v[4:5], off
	v_lshrrev_b32_e32 v4, 31, v0
	v_ashrrev_i32_e32 v0, 1, v0
	v_add_u32_e32 v236, v0, v4
	v_mul_lo_u32 v0, v236, 12
	v_sub_u32_e32 v53, v32, v0
	v_lshlrev_b32_e32 v4, 3, v53
	v_ashrrev_i32_e32 v5, 31, v4
	v_mad_i64_i32 v[6:7], s[10:11], v236, s86, v[24:25]
	v_lshlrev_b64 v[20:21], 1, v[4:5]
	v_lshl_add_u64 v[6:7], v[6:7], 0, v[20:21]
	v_mul_hi_i32 v0, v36, s9
	global_load_dwordx4 v[156:159], v[6:7], off
	v_lshrrev_b32_e32 v6, 31, v0
	v_ashrrev_i32_e32 v0, 1, v0
	v_add_u32_e32 v237, v0, v6
	v_mul_lo_u32 v0, v237, 12
	v_sub_u32_e32 v54, v36, v0
	v_lshlrev_b32_e32 v6, 3, v54
	v_ashrrev_i32_e32 v7, 31, v6
	v_mad_i64_i32 v[18:19], s[10:11], v237, s86, v[24:25]
	v_lshlrev_b64 v[26:27], 1, v[6:7]
	v_lshl_add_u64 v[18:19], v[18:19], 0, v[26:27]
	v_add_u32_e32 v0, 64, v205
	global_load_dwordx4 v[160:163], v[18:19], off
	v_mad_i64_i32 v[18:19], s[10:11], v0, s86, v[24:25]
	v_add_u32_e32 v0, 64, v236
	v_mad_i64_i32 v[22:23], s[10:11], v0, s86, v[24:25]
	v_add_u32_e32 v0, 64, v237
	v_mad_i64_i32 v[24:25], s[10:11], v0, s86, v[24:25]
	v_lshlrev_b32_e32 v0, 3, v15
	v_add_u32_e32 v15, 0x300, v15
	v_and_b32_e32 v0, 56, v0
	v_ashrrev_i32_e32 v50, 3, v15
	v_lshlrev_b32_e32 v0, 1, v0
	v_ashrrev_i32_e32 v51, 31, v50
	v_lshl_add_u64 v[206:207], s[22:23], 0, v[0:1]
	v_lshlrev_b64 v[214:215], 15, v[50:51]
	v_lshl_add_u64 v[24:25], v[24:25], 0, v[26:27]
	v_lshl_add_u64 v[28:29], v[206:207], 0, v[208:209]
	v_lshl_add_u64 v[32:33], v[206:207], 0, v[210:211]
	v_lshl_add_u64 v[36:37], v[206:207], 0, v[212:213]
	v_lshl_add_u64 v[40:41], v[206:207], 0, v[214:215]
	v_lshl_add_u64 v[16:17], v[18:19], 0, v[16:17]
	global_load_dwordx4 v[24:27], v[24:25], off
	v_lshl_add_u64 v[20:21], v[22:23], 0, v[20:21]
	global_load_dwordx4 v[28:31], v[28:29], off
	s_movk_i32 s9, 0xd0
	global_load_dwordx4 v[32:35], v[32:33], off
	v_mul_lo_u32 v15, v205, s9
	global_load_dwordx4 v[36:39], v[36:37], off
	v_lshlrev_b32_e32 v45, 4, v52
	global_load_dwordx4 v[40:43], v[40:41], off
	v_add_u32_e32 v238, v15, v45
	global_load_dwordx4 v[16:19], v[16:17], off
	v_mul_lo_u32 v15, v236, s9
	global_load_dwordx4 v[20:23], v[20:21], off
	v_lshlrev_b32_e32 v45, 4, v53
	v_add_u32_e32 v239, v15, v45
	v_mul_lo_u32 v15, v237, s9
	v_lshlrev_b32_e32 v45, 4, v54
	v_add_u32_e32 v240, v15, v45
	v_mul_lo_u32 v15, v44, s87
	v_add_u32_e32 v241, v0, v15
	v_mul_lo_u32 v15, v46, s87
	v_add_u32_e32 v242, v0, v15
	v_mul_lo_u32 v15, v48, s87
	v_add_u32_e32 v243, v0, v15
	v_mul_lo_u32 v15, v50, s87
	v_add_u32_e32 v244, v0, v15
	s_waitcnt vmcnt(9)
	ds_write_b128 v238, v[152:155]
	s_waitcnt vmcnt(8)
	ds_write_b128 v239, v[156:159]
	s_waitcnt vmcnt(7)
	ds_write_b128 v240, v[160:163]
	s_waitcnt vmcnt(1)
	ds_write_b128 v238, v[16:19] offset:31744
	s_waitcnt vmcnt(0)
	ds_write_b128 v239, v[20:23] offset:31744
	ds_write_b128 v240, v[24:27] offset:31744
	ds_write_b128 v241, v[28:31] offset:13312
	ds_write_b128 v242, v[32:35] offset:13312
	ds_write_b128 v243, v[36:39] offset:13312
	ds_write_b128 v244, v[40:43] offset:13312
	s_cbranch_scc1 .LBB0_367
; #define ATT_LOADK(rk_, k0_) { _Pragma("unroll") for (int i = 0; i < NKC; ++i) { int c = tid + 256 * i, row = c / CPR, kc = (c % CPR) * 8; rk_[i] = *(const bf16x8*)(Kp + (size_t)((k0_) + row) * ldk + kc); } }
; #define ATT_LOADV(rv_, k0_) { _Pragma("unroll") for (int i = 0; i < 4; ++i) { int c = tid + 256 * i, row = c >> 3, tc = (c & 7) * 8; rv_[i] = *(const bf16x8*)(Vt + (size_t)row * TT + (k0_) + tc); } }
; template <int DK, bool FIXED>
; DI void attn_pass(f32x16 (&O)[4], const bf16_t* __restrict__ Qw  , int ldq, const bf16_t* __restrict__ Kp, int ldk,
;                   const bf16_t* __restrict__ Vt, int ntb, int ntw, unsigned char* ldsb, float M2) {
;     ...
;   if (ntb > 2) ATT_LOADK(rk, 128)
;   ATT_LOADV(rv, 64)
;   __syncthreads();
;   {
;     f32x16 sS[2];
;     ATT_QK(sS, 0)
	v_add_u32_e32 v15, 0x80, v205
	v_mov_b64_e32 v[16:17], s[44:45]
	v_mad_i64_i32 v[18:19], s[10:11], v15, s86, v[16:17]
	v_add_u32_e32 v15, 0x80, v236
	v_mad_i64_i32 v[20:21], s[10:11], v15, s86, v[16:17]
	v_add_u32_e32 v15, 0x80, v237
	v_mad_i64_i32 v[16:17], s[10:11], v15, s86, v[16:17]
	v_lshl_add_u64 v[18:19], v[2:3], 1, v[18:19]
	v_lshl_add_u64 v[16:17], v[6:7], 1, v[16:17]
	v_lshl_add_u64 v[20:21], v[4:5], 1, v[20:21]
	global_load_dwordx4 v[152:155], v[18:19], off
	global_load_dwordx4 v[156:159], v[20:21], off
	global_load_dwordx4 v[160:163], v[16:17], off
.LBB0_367:
	s_waitcnt lgkmcnt(11)
	v_max_f32_e32 v13, v13, v13
	v_max_f32_e32 v10, v10, v10
	v_max_f32_e32 v10, v10, v13
	s_waitcnt lgkmcnt(10)
	v_max_f32_e32 v12, v12, v12
	v_max_f32_e32 v11, v11, v11
	v_max_f32_e32 v11, v11, v12
	v_mul_f32_e32 v10, 0x4168f3d7, v10
	v_mul_f32_e32 v10, v11, v10
	v_min_f32_e32 v15, 0x42700000, v10
	v_lshl_add_u64 v[10:11], s[22:23], 0, v[208:209]
	v_lshl_add_u64 v[12:13], s[22:23], 0, v[210:211]
	v_lshl_add_u64 v[10:11], v[10:11], 0, v[0:1]
	v_lshl_add_u64 v[12:13], v[12:13], 0, v[0:1]
	v_lshlrev_b32_e32 v14, 3, v14
	global_load_dwordx4 v[164:167], v[10:11], off offset:128
	global_load_dwordx4 v[168:171], v[12:13], off offset:128
	v_lshl_add_u64 v[10:11], s[22:23], 0, v[212:213]
	v_lshl_add_u64 v[12:13], s[22:23], 0, v[214:215]
	v_lshl_add_u64 v[10:11], v[10:11], 0, v[0:1]
	v_lshl_add_u64 v[12:13], v[12:13], 0, v[0:1]
	v_lshlrev_b32_e32 v0, 1, v14
	s_movk_i32 s1, 0xd0
	v_mad_u32_u24 v245, v9, s1, v0
	global_load_dwordx4 v[172:175], v[10:11], off offset:128
	global_load_dwordx4 v[176:179], v[12:13], off offset:128
	s_waitcnt lgkmcnt(0)
	s_barrier
	ds_read_b128 v[10:13], v245
	ds_read_b128 v[64:67], v245 offset:32
	v_xor_b32_e32 v16, 0x80000000, v15
	v_mov_b32_e32 v17, v16
	v_mov_b32_e32 v18, v16
	v_mov_b32_e32 v19, v16
	v_mov_b32_e32 v20, v16
	v_mov_b32_e32 v21, v16
	v_mov_b32_e32 v22, v16
	v_mov_b32_e32 v23, v16
	v_mov_b32_e32 v24, v16
	v_mov_b32_e32 v25, v16
	v_mov_b32_e32 v26, v16
	v_mov_b32_e32 v27, v16
	v_mov_b32_e32 v28, v16
	v_mov_b32_e32 v29, v16
	v_mov_b32_e32 v30, v16
	v_mov_b32_e32 v31, v16
	s_lshl_b32 s9, s0, 1
	v_ashrrev_i32_e32 v0, 7, v8
	s_waitcnt lgkmcnt(1)
	v_mfma_f32_32x32x16_bf16 v[48:63], v[10:13], v[128:131], v[16:31]
	ds_read_b128 v[10:13], v245 offset:6656
	ds_read_b128 v[68:71], v245 offset:6688
	v_add3_u32 v246, v0, s9, 1
	v_lshl_add_u64 v[216:217], v[2:3], 1, s[44:45]
	v_lshl_add_u64 v[218:219], v[4:5], 1, s[44:45]
	v_lshl_add_u64 v[220:221], v[6:7], 1, s[44:45]
	v_mul_u32_u24_e32 v247, 0x90, v9
	v_mov_b32_e32 v2, v1
	s_waitcnt lgkmcnt(2)
	v_mfma_f32_32x32x16_bf16 v[48:63], v[64:67], v[132:135], v[48:63]
	v_mov_b32_e32 v3, v1
	v_mov_b32_e32 v4, v1
	v_mov_b32_e32 v5, v1
	v_mov_b32_e32 v6, v1
	v_mov_b32_e32 v7, v1
	v_mov_b32_e32 v9, v1
	v_ashrrev_i32_e32 v203, 31, v202
	s_waitcnt lgkmcnt(1)
	v_mfma_f32_32x32x16_bf16 v[32:47], v[10:13], v[128:131], v[16:31]
	ds_read_b128 v[10:13], v245 offset:64
	ds_read_b128 v[64:67], v245 offset:96
	s_add_i32 s10, s9, 2
	s_mov_b32 s11, 4
	s_movk_i32 s34, 0x80
	s_waitcnt lgkmcnt(1)
	v_mfma_f32_32x32x16_bf16 v[48:63], v[10:13], v[136:139], v[48:63]
	s_waitcnt lgkmcnt(0)
	v_mfma_f32_32x32x16_bf16 v[48:63], v[64:67], v[140:143], v[48:63]
	ds_read_b128 v[10:13], v245 offset:128
	ds_read_b128 v[64:67], v245 offset:160
	s_waitcnt lgkmcnt(1)
	v_mfma_f32_32x32x16_bf16 v[48:63], v[10:13], v[144:147], v[48:63]
	ds_read_b128 v[10:13], v245 offset:6720
	v_mfma_f32_32x32x16_bf16 v[32:47], v[68:71], v[132:135], v[32:47]
	s_waitcnt lgkmcnt(0)
	v_mfma_f32_32x32x16_bf16 v[32:47], v[10:13], v[136:139], v[32:47]
	v_mfma_f32_32x32x16_bf16 v[48:63], v[64:67], v[148:151], v[48:63]
	ds_read_b128 v[64:67], v245 offset:6752
	ds_read_b128 v[68:71], v245 offset:6784
	ds_read_b128 v[72:75], v245 offset:6816
	s_waitcnt lgkmcnt(0)
	s_barrier
; template <int DK, bool FIXED>
; DI void attn_pass(f32x16 (&O)[4], const bf16_t* __restrict__ Qw  , int ldq, const bf16_t* __restrict__ Kp, int ldk,
;                   const bf16_t* __restrict__ Vt, int ntb, int ntw, unsigned char* ldsb, float M2) {
;     ...
; #pragma unroll
;   for (int d = 0; d < 4; ++d)
; #pragma unroll
;     for (int r = 0; r < 16; ++r) O[d][r] = 0.f;
	s_nop 6
	v_exp_f32_e32 v0, v48
	v_mfma_f32_32x32x16_bf16 v[32:47], v[64:67], v[140:143], v[32:47]
	v_exp_f32_e32 v8, v49
	v_exp_f32_e32 v10, v50
	v_exp_f32_e32 v12, v51
	v_exp_f32_e32 v14, v52
	v_exp_f32_e32 v50, v54
	v_exp_f32_e32 v51, v55
	v_exp_f32_e32 v48, v53
	v_mfma_f32_32x32x16_bf16 v[32:47], v[68:71], v[144:147], v[32:47]
	v_add_f32_e32 v11, v0, v14
	v_add_f32_e32 v15, v10, v50
	v_add_f32_e32 v49, v12, v51
	v_cvt_pk_bf16_f32 v180, v0, v8
	v_cvt_pk_bf16_f32 v181, v10, v12
	v_cvt_pk_bf16_f32 v183, v50, v51
	v_exp_f32_e32 v10, v56
	v_mfma_f32_32x32x16_bf16 v[32:47], v[72:75], v[148:151], v[32:47]
	v_exp_f32_e32 v12, v57
	v_exp_f32_e32 v0, v60
	v_exp_f32_e32 v50, v61
	v_add_f32_e32 v13, v8, v48
	v_cvt_pk_bf16_f32 v182, v14, v48
	v_exp_f32_e32 v8, v58
	v_exp_f32_e32 v14, v59
	v_exp_f32_e32 v48, v62
	v_exp_f32_e32 v56, v63
	v_pk_add_f32 v[52:53], v[10:11], v[0:1]
	v_cvt_pk_bf16_f32 v184, v10, v12
	v_cvt_pk_bf16_f32 v186, v0, v50
	v_exp_f32_e32 v0, v32
	v_exp_f32_e32 v10, v34
	v_exp_f32_e32 v32, v36
	v_exp_f32_e32 v34, v37
	v_add_f32_e32 v11, v8, v48
	v_cvt_pk_bf16_f32 v185, v8, v14
	v_exp_f32_e32 v8, v33
	v_mov_b32_e32 v51, v1
	v_pk_add_f32 v[52:53], v[52:53], v[52:53] op_sel_hi:[0,1]
	v_pk_add_f32 v[54:55], v[12:13], v[50:51]
	v_add_f32_e32 v13, v14, v56
	v_exp_f32_e32 v14, v38
	v_pk_add_f32 v[54:55], v[54:55], v[54:55] op_sel_hi:[0,1]
	v_cvt_pk_bf16_f32 v187, v48, v56
	v_exp_f32_e32 v12, v35
	v_exp_f32_e32 v48, v39
	v_add_f32_e32 v33, v0, v32
	v_cvt_pk_bf16_f32 v190, v32, v34
	v_exp_f32_e32 v32, v40
	v_exp_f32_e32 v52, v44
	v_add_f32_e32 v35, v8, v34
	v_cvt_pk_bf16_f32 v188, v0, v8
	v_exp_f32_e32 v34, v41
	v_exp_f32_e32 v0, v42
	v_exp_f32_e32 v54, v45
	v_exp_f32_e32 v40, v46
	v_add_f32_e32 v15, 0, v15
	v_exp_f32_e32 v8, v43
	v_exp_f32_e32 v41, v47
	v_add_f32_e32 v49, 0, v49
	v_pk_add_f32 v[36:37], v[10:11], v[14:15]
	v_pk_add_f32 v[38:39], v[12:13], v[48:49]
	v_pk_add_f32 v[36:37], v[36:37], v[36:37] op_sel:[0,1] op_sel_hi:[1,0]
	v_cvt_pk_bf16_f32 v189, v10, v12
	v_pk_add_f32 v[10:11], v[32:33], v[52:53]
	v_pk_add_f32 v[38:39], v[38:39], v[38:39] op_sel:[0,1] op_sel_hi:[1,0]
	v_cvt_pk_bf16_f32 v191, v14, v48
	v_pk_add_f32 v[12:13], v[34:35], v[54:55]
	v_add_f32_e32 v14, v0, v40
	v_mov_b32_e32 v15, v10
	v_mov_b32_e32 v37, v11
	v_pk_add_f32 v[222:223], v[14:15], v[36:37]
	v_add_f32_e32 v10, v8, v41
	v_mov_b32_e32 v11, v12
	v_mov_b32_e32 v39, v13
	v_mov_b32_e32 v14, v1
	v_mov_b32_e32 v15, v1
	v_pk_add_f32 v[224:225], v[10:11], v[38:39]
	v_cvt_pk_bf16_f32 v192, v32, v34
	v_cvt_pk_bf16_f32 v193, v0, v8
	v_cvt_pk_bf16_f32 v194, v52, v54
	v_cvt_pk_bf16_f32 v195, v40, v41
	v_mov_b32_e32 v0, v1
	v_mov_b32_e32 v8, v1
	v_mov_b32_e32 v10, v1
	v_mov_b32_e32 v11, v1
	v_mov_b32_e32 v12, v1
	v_mov_b32_e32 v13, v1
	v_mov_b64_e32 v[46:47], v[14:15]
	v_mov_b64_e32 v[62:63], v[14:15]
	v_mov_b64_e32 v[78:79], v[14:15]
	v_mov_b64_e32 v[94:95], v[14:15]
	v_mov_b64_e32 v[44:45], v[12:13]
	v_mov_b64_e32 v[42:43], v[10:11]
	v_mov_b64_e32 v[40:41], v[8:9]
	v_mov_b64_e32 v[38:39], v[6:7]
	v_mov_b64_e32 v[36:37], v[4:5]
	v_mov_b64_e32 v[34:35], v[2:3]
	v_mov_b64_e32 v[32:33], v[0:1]
	v_mov_b64_e32 v[60:61], v[12:13]
	v_mov_b64_e32 v[58:59], v[10:11]
	v_mov_b64_e32 v[56:57], v[8:9]
	v_mov_b64_e32 v[54:55], v[6:7]
	v_mov_b64_e32 v[52:53], v[4:5]
	v_mov_b64_e32 v[50:51], v[2:3]
	v_mov_b64_e32 v[48:49], v[0:1]
	v_mov_b64_e32 v[76:77], v[12:13]
	v_mov_b64_e32 v[74:75], v[10:11]
	v_mov_b64_e32 v[72:73], v[8:9]
	v_mov_b64_e32 v[70:71], v[6:7]
	v_mov_b64_e32 v[68:69], v[4:5]
	v_mov_b64_e32 v[66:67], v[2:3]
	v_mov_b64_e32 v[64:65], v[0:1]
	v_mov_b64_e32 v[92:93], v[12:13]
	v_mov_b64_e32 v[90:91], v[10:11]
	v_mov_b64_e32 v[88:89], v[8:9]
	v_mov_b64_e32 v[86:87], v[6:7]
	v_mov_b64_e32 v[84:85], v[4:5]
	v_mov_b64_e32 v[82:83], v[2:3]
	v_mov_b64_e32 v[80:81], v[0:1]
	s_branch .LBB0_370

.LBB0_374:
	s_add_i32 s14, s11, -1
	s_cmp_lt_u32 s14, s10
	s_cselect_b64 s[82:83], -1, 0
	s_cmp_ge_u32 s14, s10
	s_cbranch_scc1 .LBB0_377
	v_add3_u32 v0, v205, s34, 64
	v_mad_i64_i32 v[14:15], s[14:15], v0, s86, v[216:217]
	v_add3_u32 v0, v236, s34, 64
	v_mad_i64_i32 v[96:97], s[14:15], v0, s86, v[218:219]
	v_add3_u32 v0, v237, s34, 64
	global_load_dwordx4 v[152:155], v[14:15], off
	global_load_dwordx4 v[156:159], v[96:97], off
	v_mad_i64_i32 v[14:15], s[14:15], v0, s86, v[220:221]
	global_load_dwordx4 v[160:163], v[14:15], off
	v_cndmask_b32_e64 v0, 0, 1, s[0:1]
	v_cmp_ne_u32_e64 s[40:41], 1, v0
	s_andn2_b64 vcc, exec, s[0:1]
	s_cbranch_vccz .LBB0_378

.LBB0_378:
	v_lshl_add_u64 v[14:15], s[34:35], 1, v[206:207]
	v_lshl_add_u64 v[96:97], v[14:15], 0, v[214:215]
	v_lshl_add_u64 v[98:99], v[14:15], 0, v[212:213]
	v_lshl_add_u64 v[100:101], v[14:15], 0, v[210:211]
	v_lshl_add_u64 v[14:15], v[14:15], 0, v[208:209]
	global_load_dwordx4 v[164:167], v[14:15], off
	global_load_dwordx4 v[168:171], v[100:101], off
	global_load_dwordx4 v[172:175], v[98:99], off
	global_load_dwordx4 v[176:179], v[96:97], off
	v_cmp_lt_i32_e32 vcc, s12, v246
	s_and_saveexec_b64 s[0:1], vcc
	s_cbranch_execz .LBB0_384

.LBB0_387:
	v_add_u32_e32 v0, s34, v205
	v_add_u32_e32 v0, 0x80, v0
	v_mad_i64_i32 v[14:15], s[14:15], v0, s86, v[216:217]
	v_add_u32_e32 v0, s34, v236
	v_add_u32_e32 v0, 0x80, v0
	v_mad_i64_i32 v[96:97], s[14:15], v0, s86, v[218:219]
	v_add_u32_e32 v0, s34, v237
	v_add_u32_e32 v0, 0x80, v0
	global_load_dwordx4 v[152:155], v[14:15], off
	global_load_dwordx4 v[156:159], v[96:97], off
	v_mad_i64_i32 v[14:15], s[14:15], v0, s86, v[220:221]
	global_load_dwordx4 v[160:163], v[14:15], off
	s_and_b64 vcc, exec, s[0:1]
	s_cbranch_vccz .LBB0_392

.LBB0_392:
	s_add_i32 s0, s34, 64
	s_mov_b32 s1, s35
	v_lshl_add_u64 v[14:15], s[0:1], 1, v[206:207]
	v_lshl_add_u64 v[96:97], v[14:15], 0, v[214:215]
	v_lshl_add_u64 v[98:99], v[14:15], 0, v[212:213]
	v_lshl_add_u64 v[100:101], v[14:15], 0, v[210:211]
	v_lshl_add_u64 v[14:15], v[14:15], 0, v[208:209]
	global_load_dwordx4 v[164:167], v[14:15], off
	global_load_dwordx4 v[168:171], v[100:101], off
	global_load_dwordx4 v[172:175], v[98:99], off
	global_load_dwordx4 v[176:179], v[96:97], off
	v_cmp_lt_i32_e32 vcc, s13, v246
	s_and_saveexec_b64 s[0:1], vcc
	s_cbranch_execz .LBB0_369

; DI int otid() { int t = (int)__builtin_amdgcn_workitem_id_x(); asm volatile("" : "+v"(t)); return t; }
; template <int DK, bool FIXED>
; DI void attn_pass(f32x16 (&O)[4], const bf16_t* __restrict__ Qw  , int ldq, const bf16_t* __restrict__ Kp, int ldk,
;                   const bf16_t* __restrict__ Vt, int ntb, int ntw, unsigned char* ldsb, float M2) {
;     ...
;   bf16x8 qf[KS];
; #pragma unroll
;   for (int ks = 0; ks < KS; ++ks) qf[ks] = *(const bf16x8*)(Qw + (size_t)l31 * ldq + ks * 16 + hf * 8);
; #pragma unroll
;   for (int d = 0; d < 4; ++d)
; #pragma unroll
;     for (int r = 0; r < 16; ++r) O[d][r] = 0.f;
;   float ps0 = 0.f, ps1 = 0.f, ps2 = 0.f, ps3 = 0.f;
;   bf16x8 rk[NKC], rv[4];
; DI void diffmap_item(const Params& p, int l, int h, int map, int qt, unsigned char* lds) {
;     ...
;   bf16_t* DO = (bf16_t*)(p.ws + (map == 0 ? OFF_O1 : OFF_RB));
;   const int row0 = qt * 128 + wid * 32, ntb = 2 * qt + 2, ntw = 2 * qt + 1 + (wid >> 1);
;   f32x16 O[4];
;   const int lane = otid() & 63;
;   float wq = fabsf(p.dqn[l * 64 + lane]), wk = fabsf(p.dkn[l * 64 + lane]);
; #pragma unroll
;   for (int o = 32; o >= 1; o >>= 1) { wq = fmaxf(wq, __shfl_xor(wq, o)); wk = fmaxf(wk, __shfl_xor(wk, o)); }
;   const float M2 = 8.f * LOG2E * 1.03f * wq * wk;
;   const bf16_t* Qp_ = RA + (size_t)row0 * 1536 + h * 128 + map * 64; const bf16_t* Kp_ = RA + 512 + h * 128 + map * 64;
.LBB0_398:
	s_and_b64 vcc, exec, s[0:1]
	s_cbranch_vccz .LBB0_432
	v_mov_b32_e32 v66, v201
	v_mov_b32_e32 v0, v201
	v_readlane_b32 s60, v253, 60
	v_and_or_b32 v0, v0, 63, s33
	v_lshlrev_b32_e32 v0, 2, v0
	v_readlane_b32 s74, v254, 10
	v_readlane_b32 s75, v254, 11
	v_readlane_b32 s61, v253, 61
	v_readlane_b32 s62, v253, 62
	v_readlane_b32 s63, v253, 63
	v_readlane_b32 s64, v254, 0
	v_readlane_b32 s65, v254, 1
	global_load_dword v2, v0, s[74:75]
	v_readlane_b32 s66, v254, 2
	v_readlane_b32 s67, v254, 3
	v_readlane_b32 s68, v254, 4
	v_readlane_b32 s69, v254, 5
	v_readlane_b32 s70, v254, 6
	v_readlane_b32 s71, v254, 7
	v_readlane_b32 s72, v254, 8
	v_readlane_b32 s73, v254, 9
	v_readlane_b32 s60, v252, 10
	v_readlane_b32 s61, v252, 11
	v_and_b32_e32 v5, 64, v227
	v_add_u32_e32 v5, 64, v5
	v_xor_b32_e32 v6, 32, v227
	v_cmp_lt_i32_e32 vcc, v6, v5
	s_add_i32 s8, s8, s7
	global_load_dword v0, v0, s[60:61]
	v_cndmask_b32_e32 v6, v227, v6, vcc
	v_lshlrev_b32_e32 v212, 2, v6
	v_mov_b32_e32 v27, v201
	s_sub_i32 s0, 0x7f, s8
	v_mov_b32_e32 v191, v1
	v_and_b32_e32 v67, 31, v27
	v_bfe_u32 v24, v27, 5, 1
	v_lshlrev_b32_e32 v190, 4, v24
	v_add_u32_e32 v18, 0x100, v27
	v_mov_b64_e32 v[6:7], s[96:97]
	v_ashrrev_i32_e32 v16, 3, v27
	v_ashrrev_i32_e32 v17, 31, v16
	v_lshlrev_b64 v[194:195], 15, v[16:17]
	v_add_u32_e32 v17, 0x200, v27
	v_ashrrev_i32_e32 v40, 3, v17
	v_add_u32_e32 v17, 0x300, v27
	v_ashrrev_i32_e32 v42, 3, v17
	v_ashrrev_i32_e32 v41, 31, v40
	v_ashrrev_i32_e32 v43, 31, v42
	v_lshlrev_b64 v[198:199], 15, v[40:41]
	v_lshlrev_b64 v[202:203], 15, v[42:43]
	s_cmpk_eq_i32 s8, 0x7f
	v_readlane_b32 s62, v252, 12
	v_readlane_b32 s63, v252, 13
	v_readlane_b32 s64, v252, 14
	v_readlane_b32 s65, v252, 15
	v_readlane_b32 s66, v252, 16
	v_readlane_b32 s67, v252, 17
	v_readlane_b32 s68, v252, 18
	v_readlane_b32 s69, v252, 19
	v_readlane_b32 s70, v252, 20
	v_readlane_b32 s71, v252, 21
	v_readlane_b32 s72, v252, 22
	v_readlane_b32 s73, v252, 23
	v_readlane_b32 s74, v252, 24
	v_readlane_b32 s75, v252, 25
	s_waitcnt vmcnt(1)
	v_and_b32_e32 v3, 0x7fffffff, v2
	ds_bpermute_b32 v3, v212, v3
	v_max_f32_e64 v2, |v2|, |v2|
	s_waitcnt lgkmcnt(0)
	v_max_f32_e32 v3, v3, v3
	v_max_f32_e32 v2, v2, v3
	s_waitcnt vmcnt(0)
	v_and_b32_e32 v4, 0x7fffffff, v0
	ds_bpermute_b32 v3, v212, v4
	v_max_f32_e64 v0, |v0|, |v0|
	s_waitcnt lgkmcnt(0)
	v_max_f32_e32 v3, v3, v3
	v_max_f32_e32 v0, v0, v3
	v_xor_b32_e32 v3, 16, v227
	v_cmp_lt_i32_e32 vcc, v3, v5
	s_nop 1
	v_cndmask_b32_e32 v3, v227, v3, vcc
	v_lshlrev_b32_e32 v3, 2, v3
	ds_bpermute_b32 v4, v3, v2
	ds_bpermute_b32 v3, v3, v0
	s_waitcnt lgkmcnt(1)
	v_max_f32_e32 v4, v4, v4
	s_waitcnt lgkmcnt(0)
	v_max_f32_e32 v3, v3, v3
	v_max_f32_e32 v0, v0, v3
	v_xor_b32_e32 v3, 8, v227
	v_cmp_lt_i32_e32 vcc, v3, v5
	v_max_f32_e32 v2, v2, v4
	s_nop 0
	v_cndmask_b32_e32 v3, v227, v3, vcc
	v_lshlrev_b32_e32 v3, 2, v3
	ds_bpermute_b32 v4, v3, v2
	ds_bpermute_b32 v3, v3, v0
	s_waitcnt lgkmcnt(1)
	v_max_f32_e32 v4, v4, v4
	s_waitcnt lgkmcnt(0)
	v_max_f32_e32 v3, v3, v3
	v_max_f32_e32 v0, v0, v3
	v_xor_b32_e32 v3, 4, v227
	v_cmp_lt_i32_e32 vcc, v3, v5
	v_max_f32_e32 v2, v2, v4
	s_nop 0
	v_cndmask_b32_e32 v3, v227, v3, vcc
	v_lshlrev_b32_e32 v3, 2, v3
	ds_bpermute_b32 v4, v3, v2
	ds_bpermute_b32 v3, v3, v0
	s_waitcnt lgkmcnt(1)
	v_max_f32_e32 v4, v4, v4
	s_waitcnt lgkmcnt(0)
	v_max_f32_e32 v3, v3, v3
	v_max_f32_e32 v0, v0, v3
	v_xor_b32_e32 v3, 2, v227
	v_cmp_lt_i32_e32 vcc, v3, v5
	v_max_f32_e32 v2, v2, v4
	s_nop 0
	v_cndmask_b32_e32 v3, v227, v3, vcc
	v_lshlrev_b32_e32 v3, 2, v3
	ds_bpermute_b32 v4, v3, v2
	s_waitcnt lgkmcnt(0)
	v_max_f32_e32 v4, v4, v4
	v_max_f32_e32 v20, v2, v4
	ds_bpermute_b32 v2, v3, v0
	s_waitcnt lgkmcnt(0)
	v_max_f32_e32 v2, v2, v2
	v_max_f32_e32 v21, v0, v2
	v_xor_b32_e32 v0, 1, v227
	v_cmp_lt_i32_e32 vcc, v0, v5
	v_mov_b64_e32 v[2:3], s[90:91]
	s_nop 0
	v_cndmask_b32_e32 v0, v227, v0, vcc
	v_lshlrev_b32_e32 v0, 2, v0
	ds_bpermute_b32 v23, v0, v20
	ds_bpermute_b32 v22, v0, v21
	v_ashrrev_i32_e32 v0, 1, v66
	v_and_b32_e32 v0, 0xffffffe0, v0
	v_lshl_add_u32 v188, s0, 7, v0
	v_mul_u32_u24_e32 v0, 0x600, v67
	v_mad_i64_i32 v[2:3], s[10:11], v188, s57, v[2:3]
	v_lshlrev_b32_e32 v0, 1, v0
	v_lshl_add_u64 v[2:3], v[2:3], 0, v[0:1]
	v_ashrrev_i32_e32 v0, 31, v27
	v_lshrrev_b32_e32 v0, 29, v0
	v_add_u32_e32 v0, v27, v0
	v_lshl_add_u64 v[2:3], v[2:3], 0, v[190:191]
	v_ashrrev_i32_e32 v191, 3, v0
	v_and_b32_e32 v0, -8, v0
	v_sub_u32_e32 v25, v27, v0
	v_ashrrev_i32_e32 v0, 31, v18
	v_lshrrev_b32_e32 v0, 29, v0
	v_add_u32_e32 v0, v18, v0
	v_lshlrev_b32_e32 v14, 3, v25
	v_ashrrev_i32_e32 v213, 3, v0
	v_and_b32_e32 v0, -8, v0
	v_ashrrev_i32_e32 v15, 31, v14
	v_sub_u32_e32 v26, v18, v0
	global_load_dwordx4 v[128:131], v[2:3], off
	global_load_dwordx4 v[132:135], v[2:3], off offset:32
	global_load_dwordx4 v[136:139], v[2:3], off offset:64
	global_load_dwordx4 v[140:143], v[2:3], off offset:96
	v_mad_i64_i32 v[2:3], s[10:11], v191, s57, v[6:7]
	v_lshlrev_b64 v[4:5], 1, v[14:15]
	v_lshlrev_b32_e32 v64, 3, v26
	v_lshl_add_u64 v[2:3], v[2:3], 0, v[4:5]
	v_ashrrev_i32_e32 v65, 31, v64
	global_load_dwordx4 v[144:147], v[2:3], off
	v_mad_i64_i32 v[2:3], s[10:11], v213, s57, v[6:7]
	v_lshlrev_b64 v[8:9], 1, v[64:65]
	v_lshl_add_u64 v[2:3], v[2:3], 0, v[8:9]
	v_add_u32_e32 v0, 64, v191
	global_load_dwordx4 v[148:151], v[2:3], off
	v_mad_i64_i32 v[2:3], s[10:11], v0, s57, v[6:7]
	v_add_u32_e32 v0, 64, v213
	v_lshl_add_u64 v[2:3], v[2:3], 0, v[4:5]
	v_mad_i64_i32 v[6:7], s[10:11], v0, s57, v[6:7]
	v_lshlrev_b32_e32 v0, 3, v27
	global_load_dwordx4 v[2:5], v[2:3], off
	v_lshl_add_u64 v[6:7], v[6:7], 0, v[8:9]
	v_and_b32_e32 v0, 56, v0
	v_ashrrev_i32_e32 v18, 3, v18
	global_load_dwordx4 v[6:9], v[6:7], off
	v_lshlrev_b32_e32 v0, 1, v0
	v_ashrrev_i32_e32 v19, 31, v18
	v_lshl_add_u64 v[192:193], s[48:49], 0, v[0:1]
	v_lshlrev_b64 v[196:197], 15, v[18:19]
	v_lshl_add_u64 v[10:11], v[192:193], 0, v[194:195]
	v_lshl_add_u64 v[28:29], v[192:193], 0, v[196:197]
	v_lshl_add_u64 v[32:33], v[192:193], 0, v[198:199]
	v_lshl_add_u64 v[36:37], v[192:193], 0, v[202:203]
	global_load_dwordx4 v[10:13], v[10:11], off
	v_mul_lo_u32 v17, v191, s87
	global_load_dwordx4 v[28:31], v[28:29], off
	v_lshlrev_b32_e32 v19, 4, v25
	global_load_dwordx4 v[32:35], v[32:33], off
	v_add_u32_e32 v214, v17, v19
	global_load_dwordx4 v[36:39], v[36:37], off
	v_mul_lo_u32 v17, v213, s87
	v_lshlrev_b32_e32 v19, 4, v26
	v_add_u32_e32 v215, v17, v19
	s_waitcnt vmcnt(7)
; #define ATT_LOADK(rk_, k0_) { _Pragma("unroll") for (int i = 0; i < NKC; ++i) { int c = tid + 256 * i, row = c / CPR, kc = (c % CPR) * 8; rk_[i] = *(const bf16x8*)(Kp + (size_t)((k0_) + row) * ldk + kc); } }
; #define ATT_LOADV(rv_, k0_) { _Pragma("unroll") for (int i = 0; i < 4; ++i) { int c = tid + 256 * i, row = c >> 3, tc = (c & 7) * 8; rv_[i] = *(const bf16x8*)(Vt + (size_t)row * TT + (k0_) + tc); } }
; #define ATT_STOREK(rk_, buf_) { bf16_t* sK_ = (bf16_t*)(ldsb + (buf_) * ATT_BUF); _Pragma("unroll") for (int i = 0; i < NKC; ++i) { int c = tid + 256 * i, row = c / CPR, kc = (c % CPR) * 8; *(bf16x8*)(sK_ + row * KST + kc) = rk_[i]; } }
; #define ATT_STOREV(rv_, buf_) { bf16_t* sV_ = (bf16_t*)(ldsb + (buf_) * ATT_BUF + 13312); _Pragma("unroll") for (int i = 0; i < 4; ++i) { int c = tid + 256 * i, row = c >> 3, tc = (c & 7) * 8; *(bf16x8*)(sV_ + row * 72 + tc) = rv_[i]; } }
; template <int DK, bool FIXED>
; DI void attn_pass(f32x16 (&O)[4], const bf16_t* __restrict__ Qw  , int ldq, const bf16_t* __restrict__ Kp, int ldk,
;                   const bf16_t* __restrict__ Vt, int ntb, int ntw, unsigned char* ldsb, float M2) {
;     ...
;     ATT_LOADK(rk, 0) ATT_LOADK(rkb, 64) ATT_LOADV(rv, 0)
;     ATT_STOREK(rk, 0) ATT_STOREK(rkb, 1) ATT_STOREV(rv, 0)
;   }
;   if (ntb > 2) ATT_LOADK(rk, 128)
;   ATT_LOADV(rv, 64)
	ds_write_b128 v214, v[144:147]
	s_waitcnt vmcnt(6)
	ds_write_b128 v215, v[148:151]
	s_waitcnt vmcnt(5)
	ds_write_b128 v214, v[2:5] offset:31744
	s_waitcnt vmcnt(4)
	ds_write_b128 v215, v[6:9] offset:31744
	v_mul_lo_u32 v2, v16, s87
	v_add_u32_e32 v216, v0, v2
	v_mul_lo_u32 v2, v18, s87
	v_add_u32_e32 v217, v0, v2
	v_mul_lo_u32 v2, v40, s87
	v_add_u32_e32 v218, v0, v2
	v_mul_lo_u32 v2, v42, s87
	v_add_u32_e32 v219, v0, v2
	s_waitcnt vmcnt(3)
	ds_write_b128 v216, v[10:13] offset:13312
	s_waitcnt vmcnt(2)
	ds_write_b128 v217, v[28:31] offset:13312
	s_waitcnt vmcnt(1)
	ds_write_b128 v218, v[32:35] offset:13312
	s_waitcnt vmcnt(0)
	ds_write_b128 v219, v[36:39] offset:13312
	s_cbranch_scc1 .LBB0_401
	v_add_u32_e32 v4, 0x80, v191
	v_mov_b64_e32 v[2:3], s[96:97]
	v_mad_i64_i32 v[4:5], s[8:9], v4, s57, v[2:3]
	v_add_u32_e32 v6, 0x80, v213
	v_lshl_add_u64 v[4:5], v[14:15], 1, v[4:5]
	v_mad_i64_i32 v[2:3], s[8:9], v6, s57, v[2:3]
	v_lshl_add_u64 v[2:3], v[64:65], 1, v[2:3]
	global_load_dwordx4 v[144:147], v[4:5], off
	global_load_dwordx4 v[148:151], v[2:3], off
; #define ATT_LOADV(rv_, k0_) { _Pragma("unroll") for (int i = 0; i < 4; ++i) { int c = tid + 256 * i, row = c >> 3, tc = (c & 7) * 8; rv_[i] = *(const bf16x8*)(Vt + (size_t)row * TT + (k0_) + tc); } }
; template <int DK, bool FIXED>
; DI void attn_pass(f32x16 (&O)[4], const bf16_t* __restrict__ Qw  , int ldq, const bf16_t* __restrict__ Kp, int ldk,
;                   const bf16_t* __restrict__ Vt, int ntb, int ntw, unsigned char* ldsb, float M2) {
;     ...
;   ATT_LOADV(rv, 64)
;   __syncthreads();
;   {
;     f32x16 sS[2];
;     ATT_QK(sS, 0)
;     ATT_EXPG(pfA, 0) ATT_EXPG(pfA, 1) ATT_EXPG(pfA, 2) ATT_EXPG(pfA, 3)
;   }
;   __syncthreads();
.LBB0_401:
	s_waitcnt lgkmcnt(9)
	v_max_f32_e32 v2, v23, v23
	v_max_f32_e32 v3, v20, v20
	v_max_f32_e32 v2, v3, v2
	s_waitcnt lgkmcnt(8)
	v_max_f32_e32 v3, v22, v22
	v_max_f32_e32 v4, v21, v21
	v_max_f32_e32 v3, v4, v3
	v_mul_f32_e32 v2, 0x413e3475, v2
	v_mul_f32_e32 v2, v3, v2
	v_min_f32_e32 v7, 0x42700000, v2
	v_lshl_add_u64 v[2:3], s[48:49], 0, v[194:195]
	v_lshl_add_u64 v[2:3], v[2:3], 0, v[0:1]
	v_lshl_add_u64 v[4:5], s[48:49], 0, v[196:197]
	v_lshl_add_u64 v[4:5], v[4:5], 0, v[0:1]
	global_load_dwordx4 v[152:155], v[2:3], off offset:128
	global_load_dwordx4 v[156:159], v[4:5], off offset:128
	v_lshl_add_u64 v[2:3], s[48:49], 0, v[198:199]
	v_lshl_add_u64 v[2:3], v[2:3], 0, v[0:1]
	v_lshl_add_u64 v[4:5], s[48:49], 0, v[202:203]
	v_lshl_add_u64 v[4:5], v[4:5], 0, v[0:1]
	global_load_dwordx4 v[160:163], v[2:3], off offset:128
	global_load_dwordx4 v[164:167], v[4:5], off offset:128
	v_lshlrev_b32_e32 v6, 3, v24
	v_lshlrev_b32_e32 v0, 1, v6
	v_mad_u32_u24 v220, v67, s87, v0
	s_waitcnt lgkmcnt(0)
	s_barrier
	ds_read_b128 v[2:5], v220
	v_xor_b32_e32 v16, 0x80000000, v7
	v_mov_b32_e32 v17, v16
	v_mov_b32_e32 v18, v16
	v_mov_b32_e32 v19, v16
	v_mov_b32_e32 v20, v16
	v_mov_b32_e32 v21, v16
	v_mov_b32_e32 v22, v16
	v_mov_b32_e32 v23, v16
	v_mov_b32_e32 v24, v16
	v_mov_b32_e32 v25, v16
	v_mov_b32_e32 v26, v16
	v_mov_b32_e32 v27, v16
	v_mov_b32_e32 v28, v16
	v_mov_b32_e32 v29, v16
	v_mov_b32_e32 v30, v16
	v_mov_b32_e32 v31, v16
	ds_read_b128 v[6:9], v220 offset:32
	s_lshl_b32 s7, s0, 1
	s_waitcnt lgkmcnt(1)
	v_mfma_f32_32x32x16_bf16 v[48:63], v[2:5], v[128:131], v[16:31]
	ds_read_b128 v[2:5], v220 offset:4608
	ds_read_b128 v[10:13], v220 offset:4640
	v_ashrrev_i32_e32 v0, 7, v66
	v_add3_u32 v221, v0, s7, 1
	v_lshl_add_u64 v[204:205], v[14:15], 1, s[96:97]
	v_mov_b32_e32 v14, v1
	v_mov_b32_e32 v15, v1
	v_mul_u32_u24_e32 v222, 0x90, v67
	s_waitcnt lgkmcnt(1)
	v_mfma_f32_32x32x16_bf16 v[32:47], v[2:5], v[128:131], v[16:31]
	v_lshl_add_u64 v[206:207], v[64:65], 1, s[96:97]
	v_readlane_b32 s60, v254, 16
	v_ashrrev_i32_e32 v189, 31, v188
	s_add_i32 s8, s7, 2
	s_mov_b32 s9, 4
	s_movk_i32 s34, 0x80
	v_readlane_b32 s61, v254, 17
	v_mfma_f32_32x32x16_bf16 v[48:63], v[6:9], v[132:135], v[48:63]
	ds_read_b128 v[2:5], v220 offset:64
	ds_read_b128 v[6:9], v220 offset:96
	v_readlane_b32 s62, v254, 18
	v_readlane_b32 s63, v254, 19
	v_readlane_b32 s64, v254, 20
	v_readlane_b32 s65, v254, 21
	v_readlane_b32 s66, v254, 22
	v_readlane_b32 s67, v254, 23
	s_waitcnt lgkmcnt(2)
	v_mfma_f32_32x32x16_bf16 v[32:47], v[10:13], v[132:135], v[32:47]
	v_readlane_b32 s68, v254, 24
	v_readlane_b32 s69, v254, 25
	v_readlane_b32 s70, v254, 26
	v_readlane_b32 s71, v254, 27
	v_readlane_b32 s72, v254, 28
	v_readlane_b32 s73, v254, 29
	v_readlane_b32 s74, v254, 30
	s_waitcnt lgkmcnt(1)
	v_mfma_f32_32x32x16_bf16 v[48:63], v[2:5], v[136:139], v[48:63]
	ds_read_b128 v[2:5], v220 offset:4672
	ds_read_b128 v[10:13], v220 offset:4704
	v_readlane_b32 s75, v254, 31
	s_waitcnt lgkmcnt(0)
	s_barrier
	v_mfma_f32_32x32x16_bf16 v[32:47], v[2:5], v[136:139], v[32:47]
	v_mfma_f32_32x32x16_bf16 v[48:63], v[6:9], v[140:143], v[48:63]
	v_mfma_f32_32x32x16_bf16 v[32:47], v[10:13], v[140:143], v[32:47]
	s_nop 10
	v_exp_f32_e32 v0, v48
	v_exp_f32_e32 v2, v49
	v_exp_f32_e32 v8, v52
	v_exp_f32_e32 v10, v53
	v_exp_f32_e32 v4, v50
	v_exp_f32_e32 v6, v51
	v_exp_f32_e32 v11, v54
	v_exp_f32_e32 v12, v55
	v_add_f32_e32 v3, v0, v8
	v_add_f32_e32 v5, v2, v10
	v_cvt_pk_bf16_f32 v168, v0, v2
	v_exp_f32_e32 v2, v56
	v_exp_f32_e32 v0, v60
	v_add_f32_e32 v7, v4, v11
	v_cvt_pk_bf16_f32 v169, v4, v6
	v_cvt_pk_bf16_f32 v170, v8, v10
	v_exp_f32_e32 v4, v57
	v_exp_f32_e32 v10, v61
	v_add_f32_e32 v9, v6, v12
	v_exp_f32_e32 v6, v58
	v_exp_f32_e32 v8, v59
	v_exp_f32_e32 v50, v62
	v_exp_f32_e32 v51, v63
	v_cvt_pk_bf16_f32 v171, v11, v12
	v_pk_add_f32 v[12:13], v[2:3], v[0:1]
	v_mov_b32_e32 v11, v1
	v_pk_add_f32 v[12:13], v[12:13], v[12:13] op_sel_hi:[0,1]
	v_pk_add_f32 v[48:49], v[4:5], v[10:11]
	v_cvt_pk_bf16_f32 v174, v0, v10
	v_exp_f32_e32 v0, v32
	v_exp_f32_e32 v10, v33
	v_exp_f32_e32 v12, v36
	v_exp_f32_e32 v32, v37
	v_add_f32_e32 v3, v6, v50
	v_add_f32_e32 v5, v8, v51
	v_cvt_pk_bf16_f32 v172, v2, v4
	v_cvt_pk_bf16_f32 v173, v6, v8
	v_exp_f32_e32 v4, v35
	v_exp_f32_e32 v6, v38
	v_exp_f32_e32 v8, v39
	v_pk_add_f32 v[48:49], v[48:49], v[48:49] op_sel_hi:[0,1]
	v_exp_f32_e32 v2, v34
	v_add_f32_e32 v9, 0, v9
	v_add_f32_e32 v11, v0, v12
	v_add_f32_e32 v33, v10, v32
	v_cvt_pk_bf16_f32 v176, v0, v10
	v_cvt_pk_bf16_f32 v178, v12, v32
	v_exp_f32_e32 v10, v40
	v_exp_f32_e32 v32, v41
	v_exp_f32_e32 v12, v44
	v_exp_f32_e32 v48, v45
	v_pk_add_f32 v[36:37], v[4:5], v[8:9]
	v_cvt_pk_bf16_f32 v179, v6, v8
	v_exp_f32_e32 v0, v42
	v_exp_f32_e32 v8, v43
	v_exp_f32_e32 v9, v46
	v_exp_f32_e32 v38, v47
	v_add_f32_e32 v7, 0, v7
	v_pk_add_f32 v[34:35], v[2:3], v[6:7]
	v_pk_add_f32 v[36:37], v[36:37], v[36:37] op_sel:[0,1] op_sel_hi:[1,0]
	v_pk_add_f32 v[34:35], v[34:35], v[34:35] op_sel:[0,1] op_sel_hi:[1,0]
	v_cvt_pk_bf16_f32 v177, v2, v4
	v_pk_add_f32 v[2:3], v[10:11], v[12:13]
	v_pk_add_f32 v[4:5], v[32:33], v[48:49]
	v_add_f32_e32 v6, v0, v9
	v_mov_b32_e32 v7, v2
	v_mov_b32_e32 v35, v3
	v_add_f32_e32 v2, v8, v38
	v_mov_b32_e32 v3, v4
	v_mov_b32_e32 v37, v5
	v_cvt_pk_bf16_f32 v175, v50, v51
	v_pk_add_f32 v[208:209], v[6:7], v[34:35]
	v_pk_add_f32 v[210:211], v[2:3], v[36:37]
	v_cvt_pk_bf16_f32 v180, v10, v32
	v_cvt_pk_bf16_f32 v181, v0, v8
	v_cvt_pk_bf16_f32 v182, v12, v48
	v_cvt_pk_bf16_f32 v183, v9, v38
	v_mov_b32_e32 v0, v1
	v_mov_b32_e32 v2, v1
	v_mov_b32_e32 v3, v1
	v_mov_b32_e32 v4, v1
	v_mov_b32_e32 v5, v1
	v_mov_b32_e32 v6, v1
	v_mov_b32_e32 v7, v1
	v_mov_b32_e32 v8, v1
	v_mov_b32_e32 v9, v1
	v_mov_b32_e32 v10, v1
	v_mov_b32_e32 v11, v1
	v_mov_b32_e32 v12, v1
	v_mov_b32_e32 v13, v1
	v_mov_b64_e32 v[46:47], v[14:15]
	v_mov_b64_e32 v[62:63], v[14:15]
	v_mov_b64_e32 v[78:79], v[14:15]
	v_mov_b64_e32 v[94:95], v[14:15]
	v_mov_b64_e32 v[44:45], v[12:13]
	v_mov_b64_e32 v[42:43], v[10:11]
	v_mov_b64_e32 v[40:41], v[8:9]
	v_mov_b64_e32 v[38:39], v[6:7]
	v_mov_b64_e32 v[36:37], v[4:5]
	v_mov_b64_e32 v[34:35], v[2:3]
	v_mov_b64_e32 v[32:33], v[0:1]
	v_mov_b64_e32 v[60:61], v[12:13]
	v_mov_b64_e32 v[58:59], v[10:11]
	v_mov_b64_e32 v[56:57], v[8:9]
	v_mov_b64_e32 v[54:55], v[6:7]
	v_mov_b64_e32 v[52:53], v[4:5]
	v_mov_b64_e32 v[50:51], v[2:3]
	v_mov_b64_e32 v[48:49], v[0:1]
	v_mov_b64_e32 v[76:77], v[12:13]
	v_mov_b64_e32 v[74:75], v[10:11]
	v_mov_b64_e32 v[72:73], v[8:9]
	v_mov_b64_e32 v[70:71], v[6:7]
	v_mov_b64_e32 v[68:69], v[4:5]
	v_mov_b64_e32 v[66:67], v[2:3]
	v_mov_b64_e32 v[64:65], v[0:1]
	v_mov_b64_e32 v[92:93], v[12:13]
	v_mov_b64_e32 v[90:91], v[10:11]
	v_mov_b64_e32 v[88:89], v[8:9]
	v_mov_b64_e32 v[86:87], v[6:7]
	v_mov_b64_e32 v[84:85], v[4:5]
	v_mov_b64_e32 v[82:83], v[2:3]
	v_mov_b64_e32 v[80:81], v[0:1]
	s_branch .LBB0_404

.LBB0_408:
	s_add_i32 s12, s9, -1
	s_cmp_lt_u32 s12, s8
	s_cselect_b64 s[82:83], -1, 0
	s_cmp_ge_u32 s12, s8
	s_cbranch_scc1 .LBB0_411
	v_add3_u32 v0, v191, s34, 64
	v_mad_i64_i32 v[14:15], s[12:13], v0, s57, v[204:205]
	v_add3_u32 v0, v213, s34, 64
	v_mad_i64_i32 v[96:97], s[12:13], v0, s57, v[206:207]
	global_load_dwordx4 v[144:147], v[14:15], off
	global_load_dwordx4 v[148:151], v[96:97], off
	v_cndmask_b32_e64 v0, 0, 1, s[0:1]
	v_cmp_ne_u32_e64 s[40:41], 1, v0
	s_andn2_b64 vcc, exec, s[0:1]
	s_cbranch_vccz .LBB0_412

.LBB0_412:
	v_lshl_add_u64 v[14:15], s[34:35], 1, v[192:193]
	v_lshl_add_u64 v[96:97], v[14:15], 0, v[202:203]
	v_lshl_add_u64 v[98:99], v[14:15], 0, v[198:199]
	v_lshl_add_u64 v[100:101], v[14:15], 0, v[196:197]
	v_lshl_add_u64 v[14:15], v[14:15], 0, v[194:195]
	global_load_dwordx4 v[152:155], v[14:15], off
	global_load_dwordx4 v[156:159], v[100:101], off
	global_load_dwordx4 v[160:163], v[98:99], off
	global_load_dwordx4 v[164:167], v[96:97], off
	v_cmp_lt_i32_e32 vcc, s10, v221
	s_and_saveexec_b64 s[0:1], vcc
	s_cbranch_execz .LBB0_418

.LBB0_421:
	v_add_u32_e32 v0, s34, v191
	v_add_u32_e32 v0, 0x80, v0
	v_mad_i64_i32 v[14:15], s[12:13], v0, s57, v[204:205]
	v_add_u32_e32 v0, s34, v213
	v_add_u32_e32 v0, 0x80, v0
	v_mad_i64_i32 v[96:97], s[12:13], v0, s57, v[206:207]
	global_load_dwordx4 v[144:147], v[14:15], off
	global_load_dwordx4 v[148:151], v[96:97], off
	s_and_b64 vcc, exec, s[0:1]
	s_cbranch_vccz .LBB0_426

.LBB0_426:
	s_add_i32 s0, s34, 64
	s_mov_b32 s1, s35
	v_lshl_add_u64 v[14:15], s[0:1], 1, v[192:193]
	v_lshl_add_u64 v[96:97], v[14:15], 0, v[202:203]
	v_lshl_add_u64 v[98:99], v[14:15], 0, v[198:199]
	v_lshl_add_u64 v[100:101], v[14:15], 0, v[196:197]
	v_lshl_add_u64 v[14:15], v[14:15], 0, v[194:195]
	global_load_dwordx4 v[152:155], v[14:15], off
	global_load_dwordx4 v[156:159], v[100:101], off
	global_load_dwordx4 v[160:163], v[98:99], off
	global_load_dwordx4 v[164:167], v[96:97], off
	v_cmp_lt_i32_e32 vcc, s11, v221
	s_and_saveexec_b64 s[0:1], vcc
	s_cbranch_execz .LBB0_403
